# late weight conversion stores write-through as well (they ran beside the in-projection's last half round)
# speedup vs baseline: 1.4084x; 1.0022x over previous
.LBB0_111:
	v_readlane_b32 s0, v233, 31
	v_lshl_or_b32 v146, s89, 8, v150
	v_readlane_b32 s1, v233, 32
	v_lshl_add_u32 v156, s68, 8, v148
	v_ashrrev_i32_e32 v147, 31, v146
	v_mov_b64_e32 v[144:145], s[0:1]
	v_mad_i64_i32 v[154:155], s[70:71], v156, s88, v[144:145]
	v_lshlrev_b64 v[146:147], 1, v[146:147]
	v_lshl_add_u64 v[154:155], v[154:155], 0, v[146:147]
	v_cvt_pk_bf16_f32 v124, v124, v125
	v_cvt_pk_bf16_f32 v125, v126, v127
	v_cvt_pk_bf16_f32 v126, v120, v121
	v_cvt_pk_bf16_f32 v127, v122, v123
	global_store_dwordx4 v[154:155], v[124:127], off
	v_cvt_pk_bf16_f32 v112, v112, v113
	v_cvt_pk_bf16_f32 v113, v114, v115
	v_cvt_pk_bf16_f32 v114, v104, v105
	v_or_b32_e32 v104, 16, v156
	v_mad_i64_i32 v[104:105], s[70:71], v104, s88, v[144:145]
	v_cvt_pk_bf16_f32 v115, v106, v107
	global_store_dwordx4 v[154:155], v[112:115], off offset:256 sc1
	s_andn2_b64 vcc, exec, s[6:7]
	s_mov_b64 s[6:7], -1
	v_lshl_add_u64 v[112:113], v[104:105], 0, v[146:147]
	v_cvt_pk_bf16_f32 v104, v116, v117
	v_cvt_pk_bf16_f32 v105, v118, v119
	v_cvt_pk_bf16_f32 v106, v108, v109
	v_cvt_pk_bf16_f32 v107, v110, v111
	global_store_dwordx4 v[112:113], v[104:107], off
	v_cvt_pk_bf16_f32 v96, v96, v97
	v_cvt_pk_bf16_f32 v97, v98, v99
	v_cvt_pk_bf16_f32 v98, v88, v89
	v_or_b32_e32 v88, 32, v156
	v_mad_i64_i32 v[88:89], s[70:71], v88, s88, v[144:145]
	v_cvt_pk_bf16_f32 v99, v90, v91
	global_store_dwordx4 v[112:113], v[96:99], off offset:256 sc1
	s_nop 1
	v_lshl_add_u64 v[96:97], v[88:89], 0, v[146:147]
	v_cvt_pk_bf16_f32 v88, v100, v101
	v_cvt_pk_bf16_f32 v89, v102, v103
	v_cvt_pk_bf16_f32 v90, v92, v93
	v_cvt_pk_bf16_f32 v91, v94, v95
	global_store_dwordx4 v[96:97], v[88:91], off
	v_cvt_pk_bf16_f32 v80, v80, v81
	v_cvt_pk_bf16_f32 v81, v82, v83
	v_cvt_pk_bf16_f32 v82, v72, v73
	v_or_b32_e32 v72, 48, v156
	v_mad_i64_i32 v[72:73], s[70:71], v72, s88, v[144:145]
	v_cvt_pk_bf16_f32 v83, v74, v75
	global_store_dwordx4 v[96:97], v[80:83], off offset:256 sc1
	s_nop 1
	v_lshl_add_u64 v[80:81], v[72:73], 0, v[146:147]
	v_cvt_pk_bf16_f32 v72, v84, v85
	v_cvt_pk_bf16_f32 v73, v86, v87
	v_cvt_pk_bf16_f32 v74, v76, v77
	v_cvt_pk_bf16_f32 v75, v78, v79
	global_store_dwordx4 v[80:81], v[72:75], off
	v_cvt_pk_bf16_f32 v68, v68, v69
	v_cvt_pk_bf16_f32 v69, v70, v71
	v_cvt_pk_bf16_f32 v70, v64, v65
	v_add_u32_e32 v64, 0x80, v156
	v_mad_i64_i32 v[64:65], s[70:71], v64, s88, v[144:145]
	v_lshl_add_u64 v[64:65], v[64:65], 0, v[146:147]
	v_cvt_pk_bf16_f32 v71, v66, v67
	global_store_dwordx4 v[80:81], v[68:71], off offset:256 sc1
	v_cvt_pk_bf16_f32 v60, v60, v61
	v_cvt_pk_bf16_f32 v61, v62, v63
	v_cvt_pk_bf16_f32 v62, v56, v57
	v_cvt_pk_bf16_f32 v63, v58, v59
	global_store_dwordx4 v[64:65], v[60:63], off
	v_cvt_pk_bf16_f32 v48, v48, v49
	v_cvt_pk_bf16_f32 v49, v50, v51
	v_cvt_pk_bf16_f32 v50, v40, v41
	v_add_u32_e32 v40, 0x90, v156
	v_mad_i64_i32 v[40:41], s[70:71], v40, s88, v[144:145]
	v_cvt_pk_bf16_f32 v51, v42, v43
	global_store_dwordx4 v[64:65], v[48:51], off offset:256 sc1
	s_nop 1
	v_lshl_add_u64 v[48:49], v[40:41], 0, v[146:147]
	v_cvt_pk_bf16_f32 v40, v52, v53
	v_cvt_pk_bf16_f32 v41, v54, v55
	v_cvt_pk_bf16_f32 v42, v44, v45
	v_cvt_pk_bf16_f32 v43, v46, v47
	global_store_dwordx4 v[48:49], v[40:43], off
	v_cvt_pk_bf16_f32 v32, v32, v33
	v_cvt_pk_bf16_f32 v33, v34, v35
	v_cvt_pk_bf16_f32 v34, v24, v25
	v_add_u32_e32 v24, 0xa0, v156
	v_mad_i64_i32 v[24:25], s[70:71], v24, s88, v[144:145]
	v_cvt_pk_bf16_f32 v35, v26, v27
	global_store_dwordx4 v[48:49], v[32:35], off offset:256 sc1
	s_nop 1
	v_lshl_add_u64 v[32:33], v[24:25], 0, v[146:147]
	v_cvt_pk_bf16_f32 v24, v36, v37
	v_cvt_pk_bf16_f32 v25, v38, v39
	v_cvt_pk_bf16_f32 v26, v28, v29
	v_cvt_pk_bf16_f32 v27, v30, v31
	global_store_dwordx4 v[32:33], v[24:27], off
	v_cvt_pk_bf16_f32 v16, v16, v17
	v_cvt_pk_bf16_f32 v17, v18, v19
	v_cvt_pk_bf16_f32 v18, v8, v9
	v_add_u32_e32 v8, 0xb0, v156
	v_mad_i64_i32 v[8:9], s[70:71], v8, s88, v[144:145]
	v_cvt_pk_bf16_f32 v19, v10, v11
	global_store_dwordx4 v[32:33], v[16:19], off offset:256 sc1
	s_nop 1
	v_lshl_add_u64 v[16:17], v[8:9], 0, v[146:147]
	v_cvt_pk_bf16_f32 v8, v20, v21
	v_cvt_pk_bf16_f32 v9, v22, v23
	v_cvt_pk_bf16_f32 v10, v12, v13
	v_cvt_pk_bf16_f32 v11, v14, v15
	global_store_dwordx4 v[16:17], v[8:11], off
	v_cvt_pk_bf16_f32 v4, v4, v5
	v_cvt_pk_bf16_f32 v5, v6, v7
	v_cvt_pk_bf16_f32 v6, v0, v1
	v_cvt_pk_bf16_f32 v7, v2, v3
	global_store_dwordx4 v[16:17], v[4:7], off offset:256 sc1
	s_cbranch_vccnz .LBB0_104
	s_andn2_b64 vcc, exec, s[16:17]
	s_cbranch_vccnz .LBB0_103
	s_barrier
	s_branch .LBB0_103
